# v11 + even in-proj epilogue: the two ssq row ladders (load, wait, add x4) become four loads issued together with immediate offsets and a single wait
# speedup vs baseline: 1.0244x; 1.0046x over previous
; __device__ __forceinline__ bf16_t f2bf(float f) { return (bf16_t)(pk2(f, 0.f) & 0xffffu); }
; __device__ __forceinline__ float grp_sum(float v) { v += __shfl_xor(v, 16); v += __shfl_xor(v, 32); return v; }
;   __device__ __forceinline__ void operator()(const pg8::f32x4 (&acc)[2][2][4][2], const pg8::Unit& u, int wr, int wc, int fr, int fq) const {
;     int z; asm volatile("v_mov_b32 %0, 0" : "=v"(z));
;     const int gi = 4 * u.pn + wc;
;     const int row0 = u.pm * 256 + wr * 64 + fr + z;
;     float kmx_run = 0.f;
; #pragma unroll
;     for (int ai = 0; ai < 2; ++ai) {
;       float rs[4];
; #pragma unroll
;       for (int m = 0; m < 4; ++m) { const f32x4 a = *(const f32x4*)(ssq + (unsigned)(row0 + ai * 128 + m * 16) * 16 + 4 * fq); rs[m] = (a[0] + a[1]) + (a[2] + a[3]); }
; #pragma unroll
;       for (int m = 0; m < 4; ++m) rs[m] = rsqrtf(grp_sum(rs[m]) * (1.f / 1024.f) + EPS);
; #pragma unroll
;       for (int m = 0; m < 4; ++m) {
;         const int tok = row0 + ai * 128 + m * 16, bb = tok >> 13, pos = tok & (S - 1);
;         float v[2][8];
; #pragma unroll
;         for (int bj = 0; bj < 2; ++bj)
; #pragma unroll
;           for (int n = 0; n < 2; ++n)
; #pragma unroll
;             for (int c = 0; c < 4; ++c) v[bj][4 * n + c] = acc[ai][bj][m][n][c] * rs[m];
;     ...
;           const int hv = (gi - 32) >> 1, eh = (gi - 32) & 1;
;           bf16_t* dst = vtb + ((unsigned)(bb * 4 + hv) * 128 + 64 * eh + 8 * fq) * S + pos;
; #pragma unroll
;           for (int bj = 0; bj < 2; ++bj)
; #pragma unroll
;             for (int e = 0; e < 8; ++e) dst[(unsigned)(32 * bj + e) * S] = f2bf(v[bj][e]);
.LBB0_385:
	s_lshl_b32 s7, s52, 8
	v_mov_b32 v157, 0
	v_and_b32_e32 v158, 64, v197
	v_add3_u32 v205, s7, v139, v157
	v_lshlrev_b32_e32 v136, 4, v205
	v_add_u32_e32 v200, 64, v158
	v_lshl_add_u64 v[158:159], v[136:137], 2, v[144:145]
	global_load_dwordx4 v[232:235], v[158:159], off
	global_load_dwordx4 v[236:239], v[158:159], off offset:1024
	global_load_dwordx4 v[240:243], v[158:159], off offset:2048
	global_load_dwordx4 v[158:161], v[158:159], off offset:3072
	v_xor_b32_e32 v156, 16, v197
	v_cmp_lt_i32_e32 vcc, v156, v200
	v_add_u32_e32 v157, v157, v139
	v_and_b32_e32 v206, 0x7f, v157
	v_cndmask_b32_e32 v156, v197, v156, vcc
	v_lshlrev_b32_e32 v201, 2, v156
	v_xor_b32_e32 v156, 32, v197
	v_cmp_lt_i32_e32 vcc, v156, v200
	s_lshl_b32 s6, s54, 2
	s_or_b32 s64, s6, s37
	v_cndmask_b32_e32 v156, v197, v156, vcc
	v_lshlrev_b32_e32 v202, 2, v156
	s_cmp_gt_i32 s64, 7
	s_cselect_b64 s[12:13], -1, 0
	s_cmp_gt_u32 s6, 15
	s_cselect_b64 s[82:83], -1, 0
	s_cmp_gt_u32 s6, 31
	s_cselect_b64 s[80:81], -1, 0
	s_lshl_b32 s76, s64, 6
	s_and_b32 s69, s76, 0x7ff80
	s_add_i32 s69, s69, s0
	s_cmp_gt_u32 s6, 23
	s_cselect_b64 s[78:79], -1, 0
	s_cmp_lt_u32 s6, 24
	s_cselect_b64 s[6:7], -1, 0
	s_and_b64 s[8:9], s[6:7], exec
	s_movk_i32 s8, 0x1ff0
	s_cselect_b32 s8, s8, 0x1fe8
	s_add_i32 s8, s8, s64
	s_lshl_b32 s59, s8, 13
	s_add_i32 s8, s64, -8
	v_cndmask_b32_e64 v204, 1.0, v199, s[6:7]
	v_lshl_or_b32 v203, s8, 13, v138
	v_lshl_or_b32 v156, s8, 6, v138
	s_mov_b64 s[10:11], -1
	s_waitcnt vmcnt(0)
	v_mov_b32_e32 v162, v233
	v_mov_b32_e32 v163, v234
	v_mov_b32_e32 v233, v235
	v_pk_add_f32 v[162:163], v[162:163], v[232:233]
	v_mov_b32_e32 v164, v237
	v_mov_b32_e32 v165, v238
	v_mov_b32_e32 v237, v239
	v_pk_add_f32 v[164:165], v[164:165], v[236:237]
	v_mov_b32_e32 v166, v241
	v_mov_b32_e32 v167, v242
	v_mov_b32_e32 v241, v243
	v_pk_add_f32 v[166:167], v[166:167], v[240:241]
	v_mov_b32_e32 v168, v159
	v_mov_b32_e32 v169, v160
	v_mov_b32_e32 v159, v161
	v_mov_b32_e32 v160, v164
	v_mov_b32_e32 v161, v162
	v_mov_b32_e32 v162, v165
	v_pk_add_f32 v[160:161], v[160:161], v[162:163]
	ds_bpermute_b32 v163, v201, v161
	ds_bpermute_b32 v162, v201, v160
	v_pk_add_f32 v[158:159], v[168:169], v[158:159]
	s_waitcnt lgkmcnt(0)
	v_pk_add_f32 v[160:161], v[160:161], v[162:163]
	ds_bpermute_b32 v163, v202, v161
	ds_bpermute_b32 v162, v202, v160
	s_waitcnt lgkmcnt(0)
	v_pk_add_f32 v[160:161], v[160:161], v[162:163]
	s_nop 0
	v_pk_fma_f32 v[162:163], v[160:161], s[66:67], v[154:155] op_sel_hi:[1,0,0]
	v_mov_b32_e32 v161, v166
	v_mul_f32_e32 v157, 0x4b800000, v163
	v_cmp_gt_f32_e32 vcc, s3, v163
	v_mov_b32_e32 v166, v159
	v_cmp_gt_f32_e64 s[8:9], s3, v162
	v_cndmask_b32_e32 v157, v163, v157, vcc
	v_rsq_f32_e32 v157, v157
	s_nop 0
	v_mul_f32_e32 v160, 0x45800000, v157
	v_cndmask_b32_e32 v168, v157, v160, vcc
	v_mov_b32_e32 v160, v158
	v_pk_add_f32 v[158:159], v[160:161], v[166:167]
	ds_bpermute_b32 v161, v201, v159
	ds_bpermute_b32 v160, v201, v158
	v_pk_mul_f32 v[164:165], v[124:125], v[168:169] op_sel_hi:[1,0]
	v_pk_mul_f32 v[126:127], v[126:127], v[168:169] op_sel_hi:[1,0]
	v_pk_mul_f32 v[124:125], v[120:121], v[168:169] op_sel_hi:[1,0]
	v_pk_mul_f32 v[122:123], v[122:123], v[168:169] op_sel_hi:[1,0]
	s_waitcnt lgkmcnt(0)
	v_pk_add_f32 v[158:159], v[158:159], v[160:161]
	ds_bpermute_b32 v161, v202, v159
	ds_bpermute_b32 v160, v202, v158
	v_pk_mul_f32 v[120:121], v[116:117], v[168:169] op_sel_hi:[1,0]
	v_pk_mul_f32 v[118:119], v[118:119], v[168:169] op_sel_hi:[1,0]
	v_pk_mul_f32 v[116:117], v[112:113], v[168:169] op_sel_hi:[1,0]
	v_pk_mul_f32 v[114:115], v[114:115], v[168:169] op_sel_hi:[1,0]
	s_and_b64 vcc, exec, s[12:13]
	s_cbranch_vccz .LBB0_396
	s_and_b64 vcc, exec, s[82:83]
	s_cbranch_vccz .LBB0_393
	v_ashrrev_i32_e32 v157, 13, v205
	v_and_b32_e32 v163, 0x1fff, v205
	s_and_b64 vcc, exec, s[80:81]
	s_cbranch_vccz .LBB0_389
	s_lshl_b32 s10, s69, 13
	v_lshl_add_u32 v112, v157, 22, s10
	v_or_b32_e32 v112, v112, v180
	v_mov_b32_e32 v113, v137
	v_lshl_add_u64 v[112:113], v[112:113], 1, s[48:49]
	v_lshlrev_b32_e32 v166, 1, v163
	v_mov_b32_e32 v167, v137
	v_lshl_add_u64 v[112:113], v[112:113], 0, v[166:167]
	v_cvt_pk_bf16_f32 v166, v164, s0
	global_store_short v[112:113], v166, off
	v_add_co_u32_e32 v166, vcc, 0x4000, v112
	v_cvt_pk_bf16_f32 v168, v165, s0
	s_nop 0
	v_addc_co_u32_e32 v167, vcc, 0, v113, vcc
	global_store_short v[166:167], v168, off
	v_add_co_u32_e32 v166, vcc, 0x8000, v112
	v_cvt_pk_bf16_f32 v168, v126, s0
	s_nop 0
	v_addc_co_u32_e32 v167, vcc, 0, v113, vcc
	global_store_short v[166:167], v168, off
	v_add_co_u32_e32 v166, vcc, 0xc000, v112
	v_cvt_pk_bf16_f32 v168, v127, s0
	s_nop 0
	v_addc_co_u32_e32 v167, vcc, 0, v113, vcc
	s_mov_b32 s10, 0x10000
	global_store_short v[166:167], v168, off
	v_add_co_u32_e32 v166, vcc, s10, v112
	v_cvt_pk_bf16_f32 v168, v124, s0
	s_nop 0
	v_addc_co_u32_e32 v167, vcc, 0, v113, vcc
	s_mov_b32 s10, 0x14000
	global_store_short v[166:167], v168, off
	v_add_co_u32_e32 v166, vcc, s10, v112
	v_cvt_pk_bf16_f32 v168, v125, s0
	s_nop 0
	v_addc_co_u32_e32 v167, vcc, 0, v113, vcc
	s_mov_b32 s10, 0x18000
	global_store_short v[166:167], v168, off
	v_add_co_u32_e32 v166, vcc, s10, v112
	v_cvt_pk_bf16_f32 v168, v122, s0
	s_nop 0
	v_addc_co_u32_e32 v167, vcc, 0, v113, vcc
	s_mov_b32 s10, 0x1c000
	global_store_short v[166:167], v168, off
	v_add_co_u32_e32 v166, vcc, s10, v112
	v_cvt_pk_bf16_f32 v168, v123, s0
	s_nop 0
	v_addc_co_u32_e32 v167, vcc, 0, v113, vcc
	s_mov_b32 s10, 0x80000
	global_store_short v[166:167], v168, off
	v_add_co_u32_e32 v166, vcc, s10, v112
	v_cvt_pk_bf16_f32 v168, v120, s0
	s_nop 0
	v_addc_co_u32_e32 v167, vcc, 0, v113, vcc
	s_mov_b32 s10, 0x84000
	global_store_short v[166:167], v168, off
	v_add_co_u32_e32 v166, vcc, s10, v112
	v_cvt_pk_bf16_f32 v168, v121, s0
	s_nop 0
	v_addc_co_u32_e32 v167, vcc, 0, v113, vcc
	s_mov_b32 s10, 0x88000
	global_store_short v[166:167], v168, off
	v_add_co_u32_e32 v166, vcc, s10, v112
	v_cvt_pk_bf16_f32 v168, v118, s0
	s_nop 0
	v_addc_co_u32_e32 v167, vcc, 0, v113, vcc
	s_mov_b32 s10, 0x8c000
	global_store_short v[166:167], v168, off
	v_add_co_u32_e32 v166, vcc, s10, v112
	v_cvt_pk_bf16_f32 v168, v119, s0
	s_nop 0
	v_addc_co_u32_e32 v167, vcc, 0, v113, vcc
	s_mov_b32 s10, 0x90000
	global_store_short v[166:167], v168, off
	v_add_co_u32_e32 v166, vcc, s10, v112
	v_cvt_pk_bf16_f32 v168, v116, s0
	s_nop 0
	v_addc_co_u32_e32 v167, vcc, 0, v113, vcc
	s_mov_b32 s10, 0x94000
	global_store_short v[166:167], v168, off
	v_add_co_u32_e32 v166, vcc, s10, v112
	v_cvt_pk_bf16_f32 v168, v117, s0
	s_nop 0
	v_addc_co_u32_e32 v167, vcc, 0, v113, vcc
	global_store_short v[166:167], v168, off
	v_add_co_u32_e32 v166, vcc, 0x98000, v112
	v_cvt_pk_bf16_f32 v168, v114, s0
	s_nop 0
	v_addc_co_u32_e32 v167, vcc, 0, v113, vcc
	v_add_co_u32_e32 v112, vcc, 0x9c000, v112
	global_store_short v[166:167], v168, off
	v_cvt_pk_bf16_f32 v166, v115, s0
	v_addc_co_u32_e32 v113, vcc, 0, v113, vcc
	global_store_short v[112:113], v166, off
	s_mov_b64 s[10:11], 0

; __device__ __forceinline__ bf16_t f2bf(float f) { return (bf16_t)(pk2(f, 0.f) & 0xffffu); }
; __device__ __forceinline__ float grp_sum(float v) { v += __shfl_xor(v, 16); v += __shfl_xor(v, 32); return v; }
;   __device__ __forceinline__ void operator()(const pg8::f32x4 (&acc)[2][2][4][2], const pg8::Unit& u, int wr, int wc, int fr, int fq) const {
;     int z; asm volatile("v_mov_b32 %0, 0" : "=v"(z));
;     const int gi = 4 * u.pn + wc;
;     const int row0 = u.pm * 256 + wr * 64 + fr + z;
;     float kmx_run = 0.f;
; #pragma unroll
;     for (int ai = 0; ai < 2; ++ai) {
;       float rs[4];
; #pragma unroll
;       for (int m = 0; m < 4; ++m) { const f32x4 a = *(const f32x4*)(ssq + (unsigned)(row0 + ai * 128 + m * 16) * 16 + 4 * fq); rs[m] = (a[0] + a[1]) + (a[2] + a[3]); }
; #pragma unroll
;       for (int m = 0; m < 4; ++m) rs[m] = rsqrtf(grp_sum(rs[m]) * (1.f / 1024.f) + EPS);
; #pragma unroll
;       for (int m = 0; m < 4; ++m) {
;         const int tok = row0 + ai * 128 + m * 16, bb = tok >> 13, pos = tok & (S - 1);
;         float v[2][8];
; #pragma unroll
;         for (int bj = 0; bj < 2; ++bj)
; #pragma unroll
;           for (int n = 0; n < 2; ++n)
; #pragma unroll
;             for (int c = 0; c < 4; ++c) v[bj][4 * n + c] = acc[ai][bj][m][n][c] * rs[m];
;     ...
;           const int hv = (gi - 32) >> 1, eh = (gi - 32) & 1;
;           bf16_t* dst = vtb + ((unsigned)(bb * 4 + hv) * 128 + 64 * eh + 8 * fq) * S + pos;
; #pragma unroll
;           for (int bj = 0; bj < 2; ++bj)
; #pragma unroll
;             for (int e = 0; e < 8; ++e) dst[(unsigned)(32 * bj + e) * S] = f2bf(v[bj][e]);
.LBB0_437:
	s_nop 1
	v_add_u32_e32 v64, 0x800, v136
	v_mov_b32_e32 v65, v137
	v_lshl_add_u64 v[64:65], v[64:65], 2, v[144:145]
	global_load_dwordx4 v[232:235], v[64:65], off
	global_load_dwordx4 v[236:239], v[64:65], off offset:1024
	global_load_dwordx4 v[240:243], v[64:65], off offset:2048
	global_load_dwordx4 v[64:67], v[64:65], off offset:3072
	v_add_u32_e32 v86, 0x80, v205
	s_mov_b64 s[82:83], -1
	s_waitcnt vmcnt(0)
	v_mov_b32_e32 v68, v233
	v_mov_b32_e32 v69, v234
	v_mov_b32_e32 v233, v235
	v_pk_add_f32 v[68:69], v[68:69], v[232:233]
	v_mov_b32_e32 v70, v237
	v_mov_b32_e32 v71, v238
	v_mov_b32_e32 v237, v239
	v_pk_add_f32 v[70:71], v[70:71], v[236:237]
	v_add_u32_e32 v136, 0xb00, v136
	v_mov_b32_e32 v72, v241
	v_mov_b32_e32 v73, v242
	v_mov_b32_e32 v241, v243
	v_pk_add_f32 v[72:73], v[72:73], v[240:241]
	v_mov_b32_e32 v74, v65
	v_mov_b32_e32 v75, v66
	v_mov_b32_e32 v65, v67
	v_mov_b32_e32 v66, v70
	v_mov_b32_e32 v67, v68
	v_mov_b32_e32 v68, v71
	v_pk_add_f32 v[66:67], v[66:67], v[68:69]
	ds_bpermute_b32 v69, v201, v67
	ds_bpermute_b32 v68, v201, v66
	v_pk_add_f32 v[64:65], v[74:75], v[64:65]
	s_waitcnt lgkmcnt(0)
	v_pk_add_f32 v[66:67], v[66:67], v[68:69]
	ds_bpermute_b32 v69, v202, v67
	ds_bpermute_b32 v68, v202, v66
	s_waitcnt lgkmcnt(0)
	v_pk_add_f32 v[66:67], v[66:67], v[68:69]
	s_nop 0
	v_pk_fma_f32 v[68:69], v[66:67], s[66:67], v[154:155] op_sel_hi:[1,0,0]
	s_nop 0
	v_mul_f32_e32 v66, 0x4b800000, v69
	v_cmp_gt_f32_e32 vcc, s3, v69
	v_cmp_gt_f32_e64 s[12:13], s3, v68
	s_nop 0
	v_cndmask_b32_e32 v66, v69, v66, vcc
	v_rsq_f32_e32 v66, v66
	s_nop 0
	v_mul_f32_e32 v67, 0x45800000, v66
	v_cndmask_b32_e32 v74, v66, v67, vcc
	v_mov_b32_e32 v66, v64
	v_mov_b32_e32 v67, v72
	v_mov_b32_e32 v72, v65
	v_pk_add_f32 v[64:65], v[66:67], v[72:73]
	ds_bpermute_b32 v67, v201, v65
	ds_bpermute_b32 v66, v201, v64
	v_pk_mul_f32 v[70:71], v[60:61], v[74:75] op_sel_hi:[1,0]
	v_pk_mul_f32 v[62:63], v[62:63], v[74:75] op_sel_hi:[1,0]
	v_pk_mul_f32 v[60:61], v[56:57], v[74:75] op_sel_hi:[1,0]
	v_pk_mul_f32 v[58:59], v[58:59], v[74:75] op_sel_hi:[1,0]
	s_waitcnt lgkmcnt(0)
	v_pk_add_f32 v[64:65], v[64:65], v[66:67]
	ds_bpermute_b32 v67, v202, v65
	ds_bpermute_b32 v66, v202, v64
	v_pk_mul_f32 v[56:57], v[52:53], v[74:75] op_sel_hi:[1,0]
	v_pk_mul_f32 v[54:55], v[54:55], v[74:75] op_sel_hi:[1,0]
	v_pk_mul_f32 v[52:53], v[48:49], v[74:75] op_sel_hi:[1,0]
	v_pk_mul_f32 v[48:49], v[50:51], v[74:75] op_sel_hi:[1,0]
	s_and_b64 vcc, exec, s[10:11]
	s_cbranch_vccnz .LBB0_448
	s_and_b64 vcc, exec, s[8:9]
	s_cbranch_vccnz .LBB0_445
	v_ashrrev_i32_e32 v87, 13, v86
	v_and_b32_e32 v88, 0x1fff, v86
	s_andn2_b64 vcc, exec, s[80:81]
	s_cbranch_vccnz .LBB0_441
	s_lshl_b32 s71, s69, 13
	v_lshl_add_u32 v50, v87, 22, s71
	v_or_b32_e32 v136, v50, v180
	v_lshl_add_u64 v[50:51], v[136:137], 1, s[48:49]
	v_lshlrev_b32_e32 v136, 1, v88
	v_lshl_add_u64 v[50:51], v[50:51], 0, v[136:137]
	v_cvt_pk_bf16_f32 v69, v70, s0
	v_add_co_u32_e32 v72, vcc, 0x4000, v50
	global_store_short v[50:51], v69, off
	v_cvt_pk_bf16_f32 v69, v71, s0
	v_addc_co_u32_e32 v73, vcc, 0, v51, vcc
	global_store_short v[72:73], v69, off
	v_add_co_u32_e32 v72, vcc, 0x8000, v50
	v_cvt_pk_bf16_f32 v69, v62, s0
	s_nop 0
	v_addc_co_u32_e32 v73, vcc, 0, v51, vcc
	global_store_short v[72:73], v69, off
	v_add_co_u32_e32 v72, vcc, 0xc000, v50
	v_cvt_pk_bf16_f32 v69, v63, s0
	s_nop 0
	v_addc_co_u32_e32 v73, vcc, 0, v51, vcc
	s_mov_b32 s71, 0x10000
	global_store_short v[72:73], v69, off
	v_add_co_u32_e32 v72, vcc, s71, v50
	v_cvt_pk_bf16_f32 v69, v60, s0
	s_nop 0
	v_addc_co_u32_e32 v73, vcc, 0, v51, vcc
	s_mov_b32 s71, 0x14000
	global_store_short v[72:73], v69, off
	v_add_co_u32_e32 v72, vcc, s71, v50
	v_cvt_pk_bf16_f32 v69, v61, s0
	s_nop 0
	v_addc_co_u32_e32 v73, vcc, 0, v51, vcc
	s_mov_b32 s71, 0x18000
	global_store_short v[72:73], v69, off
	v_add_co_u32_e32 v72, vcc, s71, v50
	v_cvt_pk_bf16_f32 v69, v58, s0
	s_nop 0
	v_addc_co_u32_e32 v73, vcc, 0, v51, vcc
	s_mov_b32 s71, 0x1c000
	global_store_short v[72:73], v69, off
	v_add_co_u32_e32 v72, vcc, s71, v50
	v_cvt_pk_bf16_f32 v69, v59, s0
	s_nop 0
	v_addc_co_u32_e32 v73, vcc, 0, v51, vcc
	s_mov_b32 s71, 0x80000
	global_store_short v[72:73], v69, off
	v_add_co_u32_e32 v72, vcc, s71, v50
	v_cvt_pk_bf16_f32 v69, v56, s0
	s_nop 0
	v_addc_co_u32_e32 v73, vcc, 0, v51, vcc
	s_mov_b32 s71, 0x84000
	global_store_short v[72:73], v69, off
	v_add_co_u32_e32 v72, vcc, s71, v50
	v_cvt_pk_bf16_f32 v69, v57, s0
	s_nop 0
	v_addc_co_u32_e32 v73, vcc, 0, v51, vcc
	s_mov_b32 s71, 0x88000
	global_store_short v[72:73], v69, off
	v_add_co_u32_e32 v72, vcc, s71, v50
	v_cvt_pk_bf16_f32 v69, v54, s0
	s_nop 0
	v_addc_co_u32_e32 v73, vcc, 0, v51, vcc
	s_mov_b32 s71, 0x8c000
	global_store_short v[72:73], v69, off
	v_add_co_u32_e32 v72, vcc, s71, v50
	v_cvt_pk_bf16_f32 v69, v55, s0
	s_nop 0
	v_addc_co_u32_e32 v73, vcc, 0, v51, vcc
	s_mov_b32 s71, 0x90000
	global_store_short v[72:73], v69, off
	v_add_co_u32_e32 v72, vcc, s71, v50
	v_cvt_pk_bf16_f32 v69, v52, s0
	s_nop 0
	v_addc_co_u32_e32 v73, vcc, 0, v51, vcc
	s_mov_b32 s71, 0x94000
	global_store_short v[72:73], v69, off
	v_add_co_u32_e32 v72, vcc, s71, v50
	v_cvt_pk_bf16_f32 v69, v53, s0
	s_nop 0
	v_addc_co_u32_e32 v73, vcc, 0, v51, vcc
	global_store_short v[72:73], v69, off
	v_add_co_u32_e32 v72, vcc, 0x98000, v50
	v_cvt_pk_bf16_f32 v69, v48, s0
	s_nop 0
	v_addc_co_u32_e32 v73, vcc, 0, v51, vcc
	v_add_co_u32_e32 v50, vcc, 0x9c000, v50
	global_store_short v[72:73], v69, off
	v_cvt_pk_bf16_f32 v69, v49, s0
	v_addc_co_u32_e32 v51, vcc, 0, v51, vcc
	s_mov_b64 s[82:83], 0
	global_store_short v[50:51], v69, off
